# 96 designated conversion workgroups instead of 64
# baseline (speedup 1.0000x reference)
; #define LAS __attribute__((address_space(3)))
; __device__ __forceinline__ int oi(int k) { asm volatile("" : "+s"(k)); return k; }
; #define opq(p) ((p) + oz())
; __device__ __forceinline__ const float* gfp(const float* p) { ASSUME_GLOBAL(p); return p; }
;     __device__ __forceinline__ bool contig(int n0) const { return (n0 % 192) < 128; }
; #define ws opq(a.ws)
;     const int kb = item / nblk, nb = item % nblk, k0 = 64 * kb, n0 = 32 * nb;
;     if (f.contig(n0)) {
;         const float* base; int ld; float sc; f(n0, base, ld, sc); sc *= mul;
;         const int r8 = lane >> 3, c4 = (lane & 7) * 4;
;         f32x4 v[8];
; #pragma unroll
;         for (int i = 0; i < 8; ++i) v[i] = __builtin_nontemporal_load((const f32x4*)(base + (size_t)(k0 + 8 * i + r8) * ld + c4));
; __device__ __forceinline__ void cvt_moe(const Args& a, int ml, LAS float* scr, int gw, int NGW, int lane) {
;     asm volatile("" : "+v"(lane));
;     constexpr int I_GU = (DM / 64) * (2 * FFE / 32), I_D = (FFE / 64) * (DM / 32), I_E = I_GU + I_D;
;     const float* wg = gfp(a.in[oi(19)]) + (size_t)ml * NEXP * DM * FFE; const float* wu = gfp(a.in[oi(20)]) + (size_t)ml * NEXP * DM * FFE; const float* wd = gfp(a.in[oi(21)]) + (size_t)ml * NEXP * FFE * DM;
;     unsigned char* wsl = opq(a.ws); bf16_t* mgu = (bf16_t*)(wsl + WS_MGU); bf16_t* md = (bf16_t*)(wsl + WS_MD);
;     for (int it = gw; it < NEXP * I_E; it += NGW) {
;         const int e = it / I_E; int r = it % I_E;
;         if (r < I_GU) { MapGU f{wg + (size_t)e * DM * FFE, wu + (size_t)e * DM * FFE, FFE}; cvt_item<MapGU, true>(f, nullptr, DM, (bf16_t*)((unsigned char*)mgu + (size_t)e * 2 * FFE * DM), scr, r, 2 * FFE / 32, lane, W8_GU); }
;         else { r -= I_GU; MapPlain f{wd + (size_t)e * FFE * DM, DM}; cvt_item<MapPlain, true>(f, nullptr, FFE, (bf16_t*)((unsigned char*)md + (size_t)e * DM * FFE), scr, r, DM / 32, lane, W8_D); }
;     }
; }
.Lcve_go:
	v_readlane_b32 s101, v251, 2
	s_nop 3
	s_and_b32 s100, s101, 7
	s_cmp_lt_u32 s100, 3
	s_cbranch_scc0 .Lcve_done
	v_writelane_b32 v145, s8, 0
	v_writelane_b32 v145, s9, 1
	v_writelane_b32 v145, s10, 2
	v_writelane_b32 v145, s11, 3
	v_writelane_b32 v145, s12, 4
	v_writelane_b32 v145, s13, 5
	v_writelane_b32 v145, s14, 6
	v_writelane_b32 v145, s15, 7
	v_writelane_b32 v145, s16, 8
	v_writelane_b32 v145, s17, 9
	v_writelane_b32 v145, s18, 10
	v_writelane_b32 v145, s19, 11
	v_writelane_b32 v145, s20, 12
	v_writelane_b32 v145, s21, 13
	v_writelane_b32 v145, s22, 14
	v_writelane_b32 v145, s23, 15
	v_writelane_b32 v145, s24, 16
	v_writelane_b32 v145, s25, 17
	v_writelane_b32 v145, s26, 18
	v_writelane_b32 v145, s27, 19
	v_writelane_b32 v145, s28, 20
	v_writelane_b32 v145, s29, 21
	v_writelane_b32 v145, s30, 22
	v_writelane_b32 v145, s31, 23
	v_writelane_b32 v145, s32, 24
	v_writelane_b32 v145, s33, 25
	v_writelane_b32 v145, s34, 26
	v_writelane_b32 v145, s35, 27
	v_writelane_b32 v145, s36, 28
	v_writelane_b32 v145, s37, 29
	v_writelane_b32 v145, s38, 30
	v_writelane_b32 v145, s39, 31
	v_writelane_b32 v145, s40, 32
	v_writelane_b32 v145, s41, 33
	v_writelane_b32 v145, s42, 34
	v_writelane_b32 v145, s43, 35
	v_writelane_b32 v145, s44, 36
	v_writelane_b32 v145, s45, 37
	v_writelane_b32 v145, s46, 38
	v_writelane_b32 v145, s47, 39
	s_mov_b64 s[8:9], exec
	s_mov_b64 exec, -1
	v_readlane_b32 s10, v251, 6
	v_readlane_b32 s11, v251, 7
	s_nop 3
	s_load_dwordx2 s[12:13], s[10:11], 0x98
	s_load_dwordx2 s[14:15], s[10:11], 0xa0
	s_load_dwordx2 s[16:17], s[10:11], 0xa8
	s_load_dwordx2 s[18:19], s[10:11], 0xb8
	s_load_dword s45, s[10:11], 0x218
	s_waitcnt lgkmcnt(0)
	s_cmpk_lg_i32 s45, 0x100
	s_cbranch_scc1 .Lcve_fin
	v_and_b32_e32 v5, 63, v166
	v_lshrrev_b32_e32 v6, 3, v5
	v_and_b32_e32 v7, 7, v5
	v_lshlrev_b32_e32 v10, 3, v7
	v_readfirstlane_b32 s46, v166
	v_mul_u32_u24_e32 v8, 0x84, v6
	v_mul_u32_u24_e32 v9, 0x420, v7
	v_lshlrev_b32_e32 v7, 4, v7
	s_lshr_b32 s46, s46, 6
	s_lshl_b32 s47, s46, 14
	v_add3_u32 v8, v8, v7, s47
	v_lshl_add_u32 v9, v6, 2, v9
	v_add_u32_e32 v9, s47, v9
	v_add_u32_e32 v128, 0, v8
	v_add_u32_e32 v129, 1056, v8
	v_add_u32_e32 v130, 2112, v8
	v_add_u32_e32 v131, 3168, v8
	v_add_u32_e32 v132, 4224, v8
	v_add_u32_e32 v133, 5280, v8
	v_add_u32_e32 v134, 6336, v8
	v_add_u32_e32 v135, 7392, v8
	s_movk_i32 s41, 0x3800
	v_mad_u32_u24 v11, v6, s41, v7
	v_add_u32_e32 v12, 0x1c000, v11
	v_add_u32_e32 v13, 0x1c000, v12
	v_add_u32_e32 v14, 0x1c000, v13
	v_add_u32_e32 v15, 0x1c000, v14
	v_add_u32_e32 v16, 0x1c000, v15
	v_add_u32_e32 v17, 0x1c000, v16
	v_add_u32_e32 v18, 0x1c000, v17
	s_movk_i32 s41, 0x1000
	v_mad_u32_u24 v136, v6, s41, v7
	v_add_u32_e32 v137, 0x8000, v136
	v_add_u32_e32 v138, 0x8000, v137
	v_add_u32_e32 v139, 0x8000, v138
	v_add_u32_e32 v140, 0x8000, v139
	v_add_u32_e32 v141, 0x8000, v140
	v_add_u32_e32 v142, 0x8000, v141
	v_add_u32_e32 v143, 0x8000, v142
	v_lshl_add_u32 v19, v6, 10, v10
	v_add_u32_e32 v20, 0x2000, v19
	v_add_u32_e32 v21, 0x2000, v20
	v_add_u32_e32 v22, 0x2000, v21
	s_movk_i32 s41, 0xe00
	v_mad_u32_u24 v144, v6, s41, v10
	v_add_u32_e32 v23, 0x7000, v144
	v_add_u32_e32 v5, 0x7000, v23
	v_add_u32_e32 v7, 0x7000, v5
	s_lshr_b32 s42, s101, 3
	s_mul_i32 s42, s42, 3
	s_and_b32 s43, s101, 7
	s_add_u32 s42, s42, s43
	s_lshl_b32 s42, s42, 3
	s_add_u32 s20, s42, s46
	s_movk_i32 s21, 56
	s_add_u32 s22, s20, 0
	s_lshr_b32 s41, s90, 1
	s_mul_i32 s41, s41, 0x7000000
	s_waitcnt lgkmcnt(0)
	s_add_u32 s12, s12, s41
	s_addc_u32 s13, s13, 0
	s_add_u32 s14, s14, s41
	s_addc_u32 s15, s15, 0
	s_add_u32 s16, s16, s41
	s_addc_u32 s17, s17, 0

;     __device__ __forceinline__ bool contig(int n0) const { return (n0 % 192) < 128; }
;     const int kb = item / nblk, nb = item % nblk, k0 = 64 * kb, n0 = 32 * nb;
;     if (f.contig(n0)) {
;         const float* base; int ld; float sc; f(n0, base, ld, sc); sc *= mul;
; __device__ __forceinline__ void cvt_moe(const Args& a, int ml, LAS float* scr, int gw, int NGW, int lane) {
;     ...
;     for (int it = gw; it < NEXP * I_E; it += NGW) {
;         const int e = it / I_E; int r = it % I_E;
;         if (r < I_GU) { MapGU f{wg + (size_t)e * DM * FFE, wu + (size_t)e * DM * FFE, FFE}; cvt_item<MapGU, true>(f, nullptr, DM, (bf16_t*)((unsigned char*)mgu + (size_t)e * 2 * FFE * DM), scr, r, 2 * FFE / 32, lane, W8_GU); }
.Lcve_EA1:
	s_add_u32 s22, s22, 768
	s_lshr_b32 s23, s22, 8
	s_mul_i32 s23, s23, 3121
	s_lshr_b32 s23, s23, 16
	s_mul_i32 s24, s23, 5376
	s_sub_u32 s24, s22, s24
	s_cmp_lt_u32 s24, 3584
	s_cbranch_scc0 .Lcve_DB2
	s_lshr_b32 s25, s24, 5
	s_mul_i32 s25, s25, 9363
	s_lshr_b32 s25, s25, 16
	s_mul_i32 s41, s25, 224
	s_sub_u32 s41, s24, s41
	s_and_b32 s42, s41, 7
	s_cmp_lt_u32 s42, 4
	s_cselect_b32 s34, s12, s14
	s_cselect_b32 s35, s13, s15
	s_mul_i32 s43, s23, 14680064
	s_mul_i32 s44, s25, 917504
	s_add_u32 s43, s43, s44
	s_lshr_b32 s44, s41, 3
	s_lshl_b32 s44, s44, 9
	s_add_u32 s43, s43, s44
	s_and_b32 s44, s42, 3
	s_lshl_b32 s44, s44, 7
	s_add_u32 s43, s43, s44
	s_add_u32 s34, s34, s43
	s_addc_u32 s35, s35, 0
	s_mul_i32 s43, s23, 7340032
	s_lshl_b32 s44, s41, 15
	s_add_u32 s43, s43, s44
	s_lshl_b32 s44, s25, 6
	s_add_u32 s43, s43, s44
	s_add_u32 s43, s43, 0x4400000
	s_add_u32 s36, s18, s43
	s_addc_u32 s37, s19, 0
	s_mov_b32 s38, 0
	s_mov_b32 s40, 0x42800000
	s_branch .Lcve_EB2

;     __device__ __forceinline__ bool contig(int n0) const { return (n0 % 192) < 128; }
;     ...
;     if (f.contig(n0)) {
;         const float* base; int ld; float sc; f(n0, base, ld, sc); sc *= mul;
;         const int r8 = lane >> 3, c4 = (lane & 7) * 4;
;         f32x4 v[8];
; #pragma unroll
;         for (int i = 0; i < 8; ++i) v[i] = __builtin_nontemporal_load((const f32x4*)(base + (size_t)(k0 + 8 * i + r8) * ld + c4));
.Lcve_EB2:
	s_add_u32 s22, s22, 768
	s_cmp_eq_u32 s30, 0
	s_cbranch_scc0 .Lcve_iA3d
	global_load_dwordx4 v[24:27], v11, s[26:27] nt
	global_load_dwordx4 v[28:31], v12, s[26:27] nt
	global_load_dwordx4 v[32:35], v13, s[26:27] nt
	global_load_dwordx4 v[36:39], v14, s[26:27] nt
	global_load_dwordx4 v[40:43], v15, s[26:27] nt
	global_load_dwordx4 v[44:47], v16, s[26:27] nt
	global_load_dwordx4 v[48:51], v17, s[26:27] nt
	global_load_dwordx4 v[52:55], v18, s[26:27] nt
	s_branch .Lcve_iA3e
